# MFMA order per 32-MFMA segment: A-fragment-stationary Gray code with back-to-back accumulate pairs across both 16-blocks
# speedup vs baseline: 1.0242x; 1.0042x over previous
.LBB0_139:
	s_add_u32 s22, s18, 0xfff00080
	s_addc_u32 s23, s19, -1
	s_add_i32 s49, 0, 0x10000
	s_cmp_eq_u32 s48, 60
	s_cselect_b32 s25, s9, s23
	s_cselect_b32 s24, s44, s22
	s_cselect_b32 s23, s7, s47
	s_cselect_b32 s22, s45, s46
	s_add_i32 s52, 0, 0x14000
	v_add_u32_e32 v156, s49, v145
	v_add_u32_e32 v172, s52, v145
	ds_read_b128 v[140:143], v156
	ds_read_b128 v[148:151], v156 offset:1024
	ds_read_b128 v[152:155], v156 offset:2048
	ds_read_b128 v[156:159], v156 offset:3072
	ds_read_b128 v[160:163], v172
	ds_read_b128 v[164:167], v172 offset:1024
	ds_read_b128 v[168:171], v172 offset:2048
	ds_read_b128 v[190:193], v172 offset:3072
	v_lshl_add_u64 v[172:173], s[18:19], 0, v[136:137]
	s_add_i32 m0, s31, 0xc000
	ds_read_b128 v[194:197], v147
	ds_read_b128 v[198:201], v147 offset:1024
	ds_read_b128 v[202:205], v147 offset:2048
	ds_read_b128 v[206:209], v147 offset:3072
	ds_read_b128 v[228:231], v147 offset:4096
	ds_read_b128 v[232:235], v147 offset:5120
	ds_read_b128 v[236:239], v147 offset:6144
	ds_read_b128 v[240:243], v147 offset:7168
	global_load_lds_dwordx4 v[172:173], off
	v_lshl_add_u64 v[172:173], s[18:19], 0, v[138:139]
	s_add_i32 m0, s31, 0xe000
	s_nop 0
	global_load_lds_dwordx4 v[172:173], off
	s_waitcnt vmcnt(8)
	s_waitcnt lgkmcnt(0)
	s_barrier
	s_setprio 1
	s_waitcnt lgkmcnt(0)
	v_mfma_f32_16x16x32_bf16 v[126:129], v[140:143], v[194:197], v[126:129]
	v_mfma_f32_16x16x32_bf16 v[126:129], v[148:151], v[198:201], v[126:129]
	v_mfma_f32_16x16x32_bf16 v[122:125], v[156:159], v[198:201], v[122:125]
	v_mfma_f32_16x16x32_bf16 v[122:125], v[152:155], v[194:197], v[122:125]
	v_mfma_f32_16x16x32_bf16 v[114:117], v[160:163], v[194:197], v[114:117]
	v_mfma_f32_16x16x32_bf16 v[114:117], v[164:167], v[198:201], v[114:117]
	v_mfma_f32_16x16x32_bf16 v[106:109], v[190:193], v[198:201], v[106:109]
	v_mfma_f32_16x16x32_bf16 v[106:109], v[168:171], v[194:197], v[106:109]
	v_mfma_f32_16x16x32_bf16 v[90:93], v[168:171], v[202:205], v[90:93]
	v_mfma_f32_16x16x32_bf16 v[90:93], v[190:193], v[206:209], v[90:93]
	v_mfma_f32_16x16x32_bf16 v[98:101], v[164:167], v[206:209], v[98:101]
	v_mfma_f32_16x16x32_bf16 v[98:101], v[160:163], v[202:205], v[98:101]
	v_mfma_f32_16x16x32_bf16 v[110:113], v[152:155], v[202:205], v[110:113]
	v_mfma_f32_16x16x32_bf16 v[110:113], v[156:159], v[206:209], v[110:113]
	v_mfma_f32_16x16x32_bf16 v[118:121], v[148:151], v[206:209], v[118:121]
	v_mfma_f32_16x16x32_bf16 v[118:121], v[140:143], v[202:205], v[118:121]
	s_setprio 0
	s_setprio 1
	v_mfma_f32_16x16x32_bf16 v[102:105], v[140:143], v[228:231], v[102:105]
	v_mfma_f32_16x16x32_bf16 v[102:105], v[148:151], v[232:235], v[102:105]
	v_mfma_f32_16x16x32_bf16 v[94:97], v[156:159], v[232:235], v[94:97]
	v_mfma_f32_16x16x32_bf16 v[94:97], v[152:155], v[228:231], v[94:97]
	v_mfma_f32_16x16x32_bf16 v[82:85], v[160:163], v[228:231], v[82:85]
	v_mfma_f32_16x16x32_bf16 v[82:85], v[164:167], v[232:235], v[82:85]
	v_mfma_f32_16x16x32_bf16 v[74:77], v[190:193], v[232:235], v[74:77]
	v_mfma_f32_16x16x32_bf16 v[74:77], v[168:171], v[228:231], v[74:77]
	v_mfma_f32_16x16x32_bf16 v[66:69], v[168:171], v[236:239], v[66:69]
	v_mfma_f32_16x16x32_bf16 v[66:69], v[190:193], v[240:243], v[66:69]
	v_mfma_f32_16x16x32_bf16 v[70:73], v[164:167], v[240:243], v[70:73]
	v_mfma_f32_16x16x32_bf16 v[70:73], v[160:163], v[236:239], v[70:73]
	v_mfma_f32_16x16x32_bf16 v[78:81], v[152:155], v[236:239], v[78:81]
	v_mfma_f32_16x16x32_bf16 v[78:81], v[156:159], v[240:243], v[78:81]
	v_mfma_f32_16x16x32_bf16 v[86:89], v[148:151], v[240:243], v[86:89]
	v_mfma_f32_16x16x32_bf16 v[86:89], v[140:143], v[236:239], v[86:89]
	s_setprio 0
	s_barrier
	s_add_i32 s49, s49, s26
	v_lshl_add_u64 v[172:173], s[22:23], 0, v[0:1]
	s_mov_b32 m0, s49
	ds_read_b128 v[194:197], v147 offset:16384
	ds_read_b128 v[198:201], v147 offset:17408
	ds_read_b128 v[202:205], v147 offset:18432
	ds_read_b128 v[206:209], v147 offset:19456
	ds_read_b128 v[228:231], v147 offset:20480
	ds_read_b128 v[232:235], v147 offset:21504
	ds_read_b128 v[236:239], v147 offset:22528
	ds_read_b128 v[240:243], v147 offset:23552
	global_load_lds_dwordx4 v[172:173], off
	s_add_i32 m0, s49, 0x2000
	s_add_u32 s50, s22, 0x100000
	v_lshl_add_u64 v[178:179], s[22:23], 0, v[130:131]
	s_addc_u32 s51, s23, 0
	s_add_i32 s49, s52, s26
	global_load_lds_dwordx4 v[178:179], off
	v_lshl_add_u64 v[180:181], s[50:51], 0, v[0:1]
	s_mov_b32 m0, s49
	v_lshl_add_u64 v[210:211], s[24:25], 0, v[132:133]
	global_load_lds_dwordx4 v[180:181], off
	v_lshl_add_u64 v[180:181], s[50:51], 0, v[130:131]
	s_add_i32 m0, s49, 0x2000
	s_nop 0
	global_load_lds_dwordx4 v[180:181], off
	v_lshl_add_u64 v[180:181], s[24:25], 0, v[134:135]
	s_mov_b32 m0, s31
	s_nop 0
	global_load_lds_dwordx4 v[180:181], off
	s_mov_b32 m0, s36
	s_nop 0
	global_load_lds_dwordx4 v[210:211], off
	s_waitcnt vmcnt(8)
	s_waitcnt lgkmcnt(0)
	s_barrier
	s_setprio 1
	s_waitcnt lgkmcnt(0)
	v_mfma_f32_16x16x32_bf16 v[62:65], v[140:143], v[194:197], v[62:65]
	v_mfma_f32_16x16x32_bf16 v[62:65], v[148:151], v[198:201], v[62:65]
	v_mfma_f32_16x16x32_bf16 v[58:61], v[156:159], v[198:201], v[58:61]
	v_mfma_f32_16x16x32_bf16 v[58:61], v[152:155], v[194:197], v[58:61]
	v_mfma_f32_16x16x32_bf16 v[50:53], v[160:163], v[194:197], v[50:53]
	v_mfma_f32_16x16x32_bf16 v[50:53], v[164:167], v[198:201], v[50:53]
	v_mfma_f32_16x16x32_bf16 v[42:45], v[190:193], v[198:201], v[42:45]
	v_mfma_f32_16x16x32_bf16 v[42:45], v[168:171], v[194:197], v[42:45]
	v_mfma_f32_16x16x32_bf16 v[26:29], v[168:171], v[202:205], v[26:29]
	v_mfma_f32_16x16x32_bf16 v[26:29], v[190:193], v[206:209], v[26:29]
	v_mfma_f32_16x16x32_bf16 v[34:37], v[164:167], v[206:209], v[34:37]
	v_mfma_f32_16x16x32_bf16 v[34:37], v[160:163], v[202:205], v[34:37]
	v_mfma_f32_16x16x32_bf16 v[46:49], v[152:155], v[202:205], v[46:49]
	v_mfma_f32_16x16x32_bf16 v[46:49], v[156:159], v[206:209], v[46:49]
	v_mfma_f32_16x16x32_bf16 v[54:57], v[148:151], v[206:209], v[54:57]
	v_mfma_f32_16x16x32_bf16 v[54:57], v[140:143], v[202:205], v[54:57]
	s_setprio 0
	s_setprio 1
	v_mfma_f32_16x16x32_bf16 v[38:41], v[140:143], v[228:231], v[38:41]
	v_mfma_f32_16x16x32_bf16 v[38:41], v[148:151], v[232:235], v[38:41]
	v_mfma_f32_16x16x32_bf16 v[30:33], v[156:159], v[232:235], v[30:33]
	v_mfma_f32_16x16x32_bf16 v[30:33], v[152:155], v[228:231], v[30:33]
	v_mfma_f32_16x16x32_bf16 v[18:21], v[160:163], v[228:231], v[18:21]
	v_mfma_f32_16x16x32_bf16 v[18:21], v[164:167], v[232:235], v[18:21]
	v_mfma_f32_16x16x32_bf16 v[10:13], v[190:193], v[232:235], v[10:13]
	v_mfma_f32_16x16x32_bf16 v[10:13], v[168:171], v[228:231], v[10:13]
	v_mfma_f32_16x16x32_bf16 v[2:5], v[168:171], v[236:239], v[2:5]
	v_mfma_f32_16x16x32_bf16 v[2:5], v[190:193], v[240:243], v[2:5]
	v_mfma_f32_16x16x32_bf16 v[6:9], v[164:167], v[240:243], v[6:9]
	v_mfma_f32_16x16x32_bf16 v[6:9], v[160:163], v[236:239], v[6:9]
	v_mfma_f32_16x16x32_bf16 v[14:17], v[152:155], v[236:239], v[14:17]
	v_mfma_f32_16x16x32_bf16 v[14:17], v[156:159], v[240:243], v[14:17]
	v_mfma_f32_16x16x32_bf16 v[22:25], v[148:151], v[240:243], v[22:25]
	v_mfma_f32_16x16x32_bf16 v[22:25], v[140:143], v[236:239], v[22:25]
	s_setprio 0
	s_barrier
	s_add_i32 s49, 0, 0x18000
	s_add_i32 s50, 0, 0x1c000
	v_add_u32_e32 v156, s49, v145
	v_add_u32_e32 v175, s50, v145
	ds_read_b128 v[140:143], v156
	ds_read_b128 v[148:151], v156 offset:1024
	ds_read_b128 v[152:155], v156 offset:2048
	ds_read_b128 v[156:159], v156 offset:3072
	ds_read_b128 v[160:163], v175
	ds_read_b128 v[164:167], v175 offset:1024
	ds_read_b128 v[168:171], v175 offset:2048
	ds_read_b128 v[190:193], v175 offset:3072
	s_add_u32 s24, s24, 0x100000
	s_addc_u32 s25, s25, 0
	s_mov_b32 m0, s37
	v_lshl_add_u64 v[244:245], s[24:25], 0, v[134:135]
	ds_read_b128 v[194:197], v147 offset:32768
	ds_read_b128 v[198:201], v147 offset:33792
	ds_read_b128 v[202:205], v147 offset:34816
	ds_read_b128 v[206:209], v147 offset:35840
	ds_read_b128 v[228:231], v147 offset:36864
	ds_read_b128 v[232:235], v147 offset:37888
	ds_read_b128 v[236:239], v147 offset:38912
	ds_read_b128 v[240:243], v147 offset:39936
	global_load_lds_dwordx4 v[244:245], off
	v_lshl_add_u64 v[244:245], s[24:25], 0, v[132:133]
	s_mov_b32 m0, s38
	s_nop 0
	global_load_lds_dwordx4 v[244:245], off
	s_waitcnt vmcnt(8)
	s_waitcnt lgkmcnt(0)
	s_barrier
	s_setprio 1
	s_waitcnt lgkmcnt(0)
	v_mfma_f32_16x16x32_bf16 v[126:129], v[140:143], v[194:197], v[126:129]
	v_mfma_f32_16x16x32_bf16 v[126:129], v[148:151], v[198:201], v[126:129]
	v_mfma_f32_16x16x32_bf16 v[122:125], v[156:159], v[198:201], v[122:125]
	v_mfma_f32_16x16x32_bf16 v[122:125], v[152:155], v[194:197], v[122:125]
	v_mfma_f32_16x16x32_bf16 v[114:117], v[160:163], v[194:197], v[114:117]
	v_mfma_f32_16x16x32_bf16 v[114:117], v[164:167], v[198:201], v[114:117]
	v_mfma_f32_16x16x32_bf16 v[106:109], v[190:193], v[198:201], v[106:109]
	v_mfma_f32_16x16x32_bf16 v[106:109], v[168:171], v[194:197], v[106:109]
	v_mfma_f32_16x16x32_bf16 v[90:93], v[168:171], v[202:205], v[90:93]
	v_mfma_f32_16x16x32_bf16 v[90:93], v[190:193], v[206:209], v[90:93]
	v_mfma_f32_16x16x32_bf16 v[98:101], v[164:167], v[206:209], v[98:101]
	v_mfma_f32_16x16x32_bf16 v[98:101], v[160:163], v[202:205], v[98:101]
	v_mfma_f32_16x16x32_bf16 v[110:113], v[152:155], v[202:205], v[110:113]
	v_mfma_f32_16x16x32_bf16 v[110:113], v[156:159], v[206:209], v[110:113]
	v_mfma_f32_16x16x32_bf16 v[118:121], v[148:151], v[206:209], v[118:121]
	v_mfma_f32_16x16x32_bf16 v[118:121], v[140:143], v[202:205], v[118:121]
	s_setprio 0
	s_setprio 1
	v_mfma_f32_16x16x32_bf16 v[102:105], v[140:143], v[228:231], v[102:105]
	v_mfma_f32_16x16x32_bf16 v[102:105], v[148:151], v[232:235], v[102:105]
	v_mfma_f32_16x16x32_bf16 v[94:97], v[156:159], v[232:235], v[94:97]
	v_mfma_f32_16x16x32_bf16 v[94:97], v[152:155], v[228:231], v[94:97]
	v_mfma_f32_16x16x32_bf16 v[82:85], v[160:163], v[228:231], v[82:85]
	v_mfma_f32_16x16x32_bf16 v[82:85], v[164:167], v[232:235], v[82:85]
	v_mfma_f32_16x16x32_bf16 v[74:77], v[190:193], v[232:235], v[74:77]
	v_mfma_f32_16x16x32_bf16 v[74:77], v[168:171], v[228:231], v[74:77]
	v_mfma_f32_16x16x32_bf16 v[66:69], v[168:171], v[236:239], v[66:69]
	v_mfma_f32_16x16x32_bf16 v[66:69], v[190:193], v[240:243], v[66:69]
	v_mfma_f32_16x16x32_bf16 v[70:73], v[164:167], v[240:243], v[70:73]
	v_mfma_f32_16x16x32_bf16 v[70:73], v[160:163], v[236:239], v[70:73]
	v_mfma_f32_16x16x32_bf16 v[78:81], v[152:155], v[236:239], v[78:81]
	v_mfma_f32_16x16x32_bf16 v[78:81], v[156:159], v[240:243], v[78:81]
	v_mfma_f32_16x16x32_bf16 v[86:89], v[148:151], v[240:243], v[86:89]
	v_mfma_f32_16x16x32_bf16 v[86:89], v[140:143], v[236:239], v[86:89]
	s_setprio 0
	s_barrier
	s_add_i32 s24, s49, s26
	v_lshl_add_u64 v[172:173], v[172:173], 0, s[34:35]
	s_mov_b32 m0, s24
	ds_read_b128 v[194:197], v147 offset:49152
	ds_read_b128 v[198:201], v147 offset:50176
	ds_read_b128 v[202:205], v147 offset:51200
	ds_read_b128 v[206:209], v147 offset:52224
	ds_read_b128 v[228:231], v147 offset:53248
	ds_read_b128 v[232:235], v147 offset:54272
	ds_read_b128 v[236:239], v147 offset:55296
	ds_read_b128 v[240:243], v147 offset:56320
	global_load_lds_dwordx4 v[172:173], off
	s_add_i32 m0, s24, 0x2000
	s_add_u32 s22, s22, 0x100080
	v_lshl_add_u64 v[172:173], v[178:179], 0, s[34:35]
	s_addc_u32 s23, s23, 0
	s_add_i32 s24, s50, s26
	global_load_lds_dwordx4 v[172:173], off
	v_lshl_add_u64 v[172:173], s[22:23], 0, v[0:1]
	s_mov_b32 m0, s24
	s_nop 0
	global_load_lds_dwordx4 v[172:173], off
	v_lshl_add_u64 v[172:173], s[22:23], 0, v[130:131]
	s_add_i32 m0, s24, 0x2000
	s_nop 0
	global_load_lds_dwordx4 v[172:173], off
	v_lshl_add_u64 v[172:173], v[180:181], 0, s[34:35]
	s_mov_b32 m0, s39
	s_nop 0
	global_load_lds_dwordx4 v[172:173], off
	v_lshl_add_u64 v[172:173], v[210:211], 0, s[34:35]
	s_mov_b32 m0, s40
	s_nop 0
	global_load_lds_dwordx4 v[172:173], off
	s_waitcnt vmcnt(8)
	s_waitcnt lgkmcnt(0)
	s_barrier
	s_setprio 1
	s_waitcnt lgkmcnt(0)
	v_mfma_f32_16x16x32_bf16 v[62:65], v[140:143], v[194:197], v[62:65]
	v_mfma_f32_16x16x32_bf16 v[62:65], v[148:151], v[198:201], v[62:65]
	v_mfma_f32_16x16x32_bf16 v[58:61], v[156:159], v[198:201], v[58:61]
	v_mfma_f32_16x16x32_bf16 v[58:61], v[152:155], v[194:197], v[58:61]
	v_mfma_f32_16x16x32_bf16 v[50:53], v[160:163], v[194:197], v[50:53]
	v_mfma_f32_16x16x32_bf16 v[50:53], v[164:167], v[198:201], v[50:53]
	v_mfma_f32_16x16x32_bf16 v[42:45], v[190:193], v[198:201], v[42:45]
	v_mfma_f32_16x16x32_bf16 v[42:45], v[168:171], v[194:197], v[42:45]
	v_mfma_f32_16x16x32_bf16 v[26:29], v[168:171], v[202:205], v[26:29]
	v_mfma_f32_16x16x32_bf16 v[26:29], v[190:193], v[206:209], v[26:29]
	v_mfma_f32_16x16x32_bf16 v[34:37], v[164:167], v[206:209], v[34:37]
	v_mfma_f32_16x16x32_bf16 v[34:37], v[160:163], v[202:205], v[34:37]
	v_mfma_f32_16x16x32_bf16 v[46:49], v[152:155], v[202:205], v[46:49]
	v_mfma_f32_16x16x32_bf16 v[46:49], v[156:159], v[206:209], v[46:49]
	v_mfma_f32_16x16x32_bf16 v[54:57], v[148:151], v[206:209], v[54:57]
	v_mfma_f32_16x16x32_bf16 v[54:57], v[140:143], v[202:205], v[54:57]
	s_setprio 0
	s_setprio 1
	v_mfma_f32_16x16x32_bf16 v[38:41], v[140:143], v[228:231], v[38:41]
	v_mfma_f32_16x16x32_bf16 v[38:41], v[148:151], v[232:235], v[38:41]
	v_mfma_f32_16x16x32_bf16 v[30:33], v[156:159], v[232:235], v[30:33]
	v_mfma_f32_16x16x32_bf16 v[30:33], v[152:155], v[228:231], v[30:33]
	v_mfma_f32_16x16x32_bf16 v[18:21], v[160:163], v[228:231], v[18:21]
	v_mfma_f32_16x16x32_bf16 v[18:21], v[164:167], v[232:235], v[18:21]
	v_mfma_f32_16x16x32_bf16 v[10:13], v[190:193], v[232:235], v[10:13]
	v_mfma_f32_16x16x32_bf16 v[10:13], v[168:171], v[228:231], v[10:13]
	v_mfma_f32_16x16x32_bf16 v[2:5], v[168:171], v[236:239], v[2:5]
	v_mfma_f32_16x16x32_bf16 v[2:5], v[190:193], v[240:243], v[2:5]
	v_mfma_f32_16x16x32_bf16 v[6:9], v[164:167], v[240:243], v[6:9]
	v_mfma_f32_16x16x32_bf16 v[6:9], v[160:163], v[236:239], v[6:9]
	v_mfma_f32_16x16x32_bf16 v[14:17], v[152:155], v[236:239], v[14:17]
	v_mfma_f32_16x16x32_bf16 v[14:17], v[156:159], v[240:243], v[14:17]
	v_mfma_f32_16x16x32_bf16 v[22:25], v[148:151], v[240:243], v[22:25]
	v_mfma_f32_16x16x32_bf16 v[22:25], v[140:143], v[236:239], v[22:25]
	s_setprio 0
	s_barrier
	s_add_i32 s48, s48, 2
	s_add_u32 s18, s18, 0x100
	s_addc_u32 s19, s19, 0
	s_add_u32 s46, s46, 0x100
	s_addc_u32 s47, s47, 0
	s_cmp_gt_u32 s48, 61
	s_cbranch_scc0 .LBB0_139
	s_and_b64 vcc, exec, s[4:5]
	s_cbranch_vccz .LBB0_142
	s_barrier

.LBB0_575:
	s_add_u32 s22, s18, 0xfff00080
	s_addc_u32 s23, s19, -1
	s_add_i32 s53, 0, 0x10000
	s_cmp_eq_u32 s52, 60
	s_cselect_b32 s25, s9, s23
	s_cselect_b32 s24, s48, s22
	v_add_u32_e32 v140, s53, v143
	s_cselect_b32 s23, s7, s51
	s_cselect_b32 s22, s49, s50
	s_add_i32 s56, 0, 0x14000
	ds_read_b128 v[146:149], v140
	ds_read_b128 v[150:153], v140 offset:1024
	ds_read_b128 v[154:157], v140 offset:2048
	ds_read_b128 v[158:161], v140 offset:3072
	v_add_u32_e32 v140, s56, v143
	ds_read_b128 v[162:165], v140
	ds_read_b128 v[166:169], v140 offset:1024
	ds_read_b128 v[170:173], v140 offset:2048
	ds_read_b128 v[178:181], v140 offset:3072
	v_lshl_add_u64 v[140:141], s[18:19], 0, v[136:137]
	s_add_i32 m0, s39, 0xc000
	ds_read_b128 v[190:193], v145
	ds_read_b128 v[194:197], v145 offset:1024
	ds_read_b128 v[198:201], v145 offset:2048
	ds_read_b128 v[202:205], v145 offset:3072
	ds_read_b128 v[206:209], v145 offset:4096
	ds_read_b128 v[228:231], v145 offset:5120
	ds_read_b128 v[232:235], v145 offset:6144
	ds_read_b128 v[236:239], v145 offset:7168
	global_load_lds_dwordx4 v[140:141], off
	v_lshl_add_u64 v[140:141], s[18:19], 0, v[138:139]
	s_add_i32 m0, s39, 0xe000
	s_nop 0
	global_load_lds_dwordx4 v[140:141], off
	s_waitcnt vmcnt(8)
	s_waitcnt lgkmcnt(0)
	s_barrier
	s_setprio 1
	s_waitcnt lgkmcnt(0)
	v_mfma_f32_16x16x32_bf16 v[126:129], v[146:149], v[190:193], v[126:129]
	v_mfma_f32_16x16x32_bf16 v[126:129], v[150:153], v[194:197], v[126:129]
	v_mfma_f32_16x16x32_bf16 v[122:125], v[158:161], v[194:197], v[122:125]
	v_mfma_f32_16x16x32_bf16 v[122:125], v[154:157], v[190:193], v[122:125]
	v_mfma_f32_16x16x32_bf16 v[114:117], v[162:165], v[190:193], v[114:117]
	v_mfma_f32_16x16x32_bf16 v[114:117], v[166:169], v[194:197], v[114:117]
	v_mfma_f32_16x16x32_bf16 v[106:109], v[178:181], v[194:197], v[106:109]
	v_mfma_f32_16x16x32_bf16 v[106:109], v[170:173], v[190:193], v[106:109]
	v_mfma_f32_16x16x32_bf16 v[90:93], v[170:173], v[198:201], v[90:93]
	v_mfma_f32_16x16x32_bf16 v[90:93], v[178:181], v[202:205], v[90:93]
	v_mfma_f32_16x16x32_bf16 v[98:101], v[166:169], v[202:205], v[98:101]
	v_mfma_f32_16x16x32_bf16 v[98:101], v[162:165], v[198:201], v[98:101]
	v_mfma_f32_16x16x32_bf16 v[110:113], v[154:157], v[198:201], v[110:113]
	v_mfma_f32_16x16x32_bf16 v[110:113], v[158:161], v[202:205], v[110:113]
	v_mfma_f32_16x16x32_bf16 v[118:121], v[150:153], v[202:205], v[118:121]
	v_mfma_f32_16x16x32_bf16 v[118:121], v[146:149], v[198:201], v[118:121]
	s_setprio 0
	s_setprio 1
	v_mfma_f32_16x16x32_bf16 v[102:105], v[146:149], v[206:209], v[102:105]
	v_mfma_f32_16x16x32_bf16 v[102:105], v[150:153], v[228:231], v[102:105]
	v_mfma_f32_16x16x32_bf16 v[94:97], v[158:161], v[228:231], v[94:97]
	v_mfma_f32_16x16x32_bf16 v[94:97], v[154:157], v[206:209], v[94:97]
	v_mfma_f32_16x16x32_bf16 v[82:85], v[162:165], v[206:209], v[82:85]
	v_mfma_f32_16x16x32_bf16 v[82:85], v[166:169], v[228:231], v[82:85]
	v_mfma_f32_16x16x32_bf16 v[74:77], v[178:181], v[228:231], v[74:77]
	v_mfma_f32_16x16x32_bf16 v[74:77], v[170:173], v[206:209], v[74:77]
	v_mfma_f32_16x16x32_bf16 v[66:69], v[170:173], v[232:235], v[66:69]
	v_mfma_f32_16x16x32_bf16 v[66:69], v[178:181], v[236:239], v[66:69]
	v_mfma_f32_16x16x32_bf16 v[70:73], v[166:169], v[236:239], v[70:73]
	v_mfma_f32_16x16x32_bf16 v[70:73], v[162:165], v[232:235], v[70:73]
	v_mfma_f32_16x16x32_bf16 v[78:81], v[154:157], v[232:235], v[78:81]
	v_mfma_f32_16x16x32_bf16 v[78:81], v[158:161], v[236:239], v[78:81]
	v_mfma_f32_16x16x32_bf16 v[86:89], v[150:153], v[236:239], v[86:89]
	v_mfma_f32_16x16x32_bf16 v[86:89], v[146:149], v[232:235], v[86:89]
	s_setprio 0
	s_barrier
	s_add_i32 s53, s53, s38
	v_lshl_add_u64 v[140:141], s[22:23], 0, v[0:1]
	s_mov_b32 m0, s53
	ds_read_b128 v[190:193], v145 offset:16384
	ds_read_b128 v[194:197], v145 offset:17408
	ds_read_b128 v[198:201], v145 offset:18432
	ds_read_b128 v[202:205], v145 offset:19456
	ds_read_b128 v[206:209], v145 offset:20480
	ds_read_b128 v[228:231], v145 offset:21504
	ds_read_b128 v[232:235], v145 offset:22528
	ds_read_b128 v[236:239], v145 offset:23552
	global_load_lds_dwordx4 v[140:141], off
	s_add_i32 m0, s53, 0x2000
	s_add_u32 s54, s22, 0x100000
	v_lshl_add_u64 v[186:187], s[22:23], 0, v[130:131]
	s_addc_u32 s55, s23, 0
	s_add_i32 s53, s56, s38
	global_load_lds_dwordx4 v[186:187], off
	v_lshl_add_u64 v[188:189], s[54:55], 0, v[0:1]
	s_mov_b32 m0, s53
	v_lshl_add_u64 v[210:211], s[24:25], 0, v[132:133]
	global_load_lds_dwordx4 v[188:189], off
	v_lshl_add_u64 v[188:189], s[54:55], 0, v[130:131]
	s_add_i32 m0, s53, 0x2000
	s_nop 0
	global_load_lds_dwordx4 v[188:189], off
	v_lshl_add_u64 v[188:189], s[24:25], 0, v[134:135]
	s_mov_b32 m0, s39
	s_nop 0
	global_load_lds_dwordx4 v[188:189], off
	s_mov_b32 m0, s40
	s_nop 0
	global_load_lds_dwordx4 v[210:211], off
	s_waitcnt vmcnt(8)
	s_waitcnt lgkmcnt(0)
	s_barrier
	s_setprio 1
	s_waitcnt lgkmcnt(0)
	v_mfma_f32_16x16x32_bf16 v[62:65], v[146:149], v[190:193], v[62:65]
	v_mfma_f32_16x16x32_bf16 v[62:65], v[150:153], v[194:197], v[62:65]
	v_mfma_f32_16x16x32_bf16 v[58:61], v[158:161], v[194:197], v[58:61]
	v_mfma_f32_16x16x32_bf16 v[58:61], v[154:157], v[190:193], v[58:61]
	v_mfma_f32_16x16x32_bf16 v[50:53], v[162:165], v[190:193], v[50:53]
	v_mfma_f32_16x16x32_bf16 v[50:53], v[166:169], v[194:197], v[50:53]
	v_mfma_f32_16x16x32_bf16 v[42:45], v[178:181], v[194:197], v[42:45]
	v_mfma_f32_16x16x32_bf16 v[42:45], v[170:173], v[190:193], v[42:45]
	v_mfma_f32_16x16x32_bf16 v[26:29], v[170:173], v[198:201], v[26:29]
	v_mfma_f32_16x16x32_bf16 v[26:29], v[178:181], v[202:205], v[26:29]
	v_mfma_f32_16x16x32_bf16 v[34:37], v[166:169], v[202:205], v[34:37]
	v_mfma_f32_16x16x32_bf16 v[34:37], v[162:165], v[198:201], v[34:37]
	v_mfma_f32_16x16x32_bf16 v[46:49], v[154:157], v[198:201], v[46:49]
	v_mfma_f32_16x16x32_bf16 v[46:49], v[158:161], v[202:205], v[46:49]
	v_mfma_f32_16x16x32_bf16 v[54:57], v[150:153], v[202:205], v[54:57]
	v_mfma_f32_16x16x32_bf16 v[54:57], v[146:149], v[198:201], v[54:57]
	s_setprio 0
	s_setprio 1
	v_mfma_f32_16x16x32_bf16 v[38:41], v[146:149], v[206:209], v[38:41]
	v_mfma_f32_16x16x32_bf16 v[38:41], v[150:153], v[228:231], v[38:41]
	v_mfma_f32_16x16x32_bf16 v[30:33], v[158:161], v[228:231], v[30:33]
	v_mfma_f32_16x16x32_bf16 v[30:33], v[154:157], v[206:209], v[30:33]
	v_mfma_f32_16x16x32_bf16 v[18:21], v[162:165], v[206:209], v[18:21]
	v_mfma_f32_16x16x32_bf16 v[18:21], v[166:169], v[228:231], v[18:21]
	v_mfma_f32_16x16x32_bf16 v[10:13], v[178:181], v[228:231], v[10:13]
	v_mfma_f32_16x16x32_bf16 v[10:13], v[170:173], v[206:209], v[10:13]
	v_mfma_f32_16x16x32_bf16 v[2:5], v[170:173], v[232:235], v[2:5]
	v_mfma_f32_16x16x32_bf16 v[2:5], v[178:181], v[236:239], v[2:5]
	v_mfma_f32_16x16x32_bf16 v[6:9], v[166:169], v[236:239], v[6:9]
	v_mfma_f32_16x16x32_bf16 v[6:9], v[162:165], v[232:235], v[6:9]
	v_mfma_f32_16x16x32_bf16 v[14:17], v[154:157], v[232:235], v[14:17]
	v_mfma_f32_16x16x32_bf16 v[14:17], v[158:161], v[236:239], v[14:17]
	v_mfma_f32_16x16x32_bf16 v[22:25], v[150:153], v[236:239], v[22:25]
	v_mfma_f32_16x16x32_bf16 v[22:25], v[146:149], v[232:235], v[22:25]
	s_setprio 0
	s_barrier
	s_add_i32 s53, 0, 0x18000
	s_add_i32 s54, 0, 0x1c000
	v_add_u32_e32 v158, s53, v143
	v_add_u32_e32 v175, s54, v143
	ds_read_b128 v[146:149], v158
	ds_read_b128 v[150:153], v158 offset:1024
	ds_read_b128 v[154:157], v158 offset:2048
	ds_read_b128 v[158:161], v158 offset:3072
	ds_read_b128 v[162:165], v175
	ds_read_b128 v[166:169], v175 offset:1024
	ds_read_b128 v[170:173], v175 offset:2048
	ds_read_b128 v[178:181], v175 offset:3072
	s_add_u32 s24, s24, 0x100000
	s_addc_u32 s25, s25, 0
	s_mov_b32 m0, s41
	v_lshl_add_u64 v[226:227], s[24:25], 0, v[134:135]
	ds_read_b128 v[190:193], v145 offset:32768
	ds_read_b128 v[194:197], v145 offset:33792
	ds_read_b128 v[198:201], v145 offset:34816
	ds_read_b128 v[202:205], v145 offset:35840
	ds_read_b128 v[206:209], v145 offset:36864
	ds_read_b128 v[228:231], v145 offset:37888
	ds_read_b128 v[232:235], v145 offset:38912
	ds_read_b128 v[236:239], v145 offset:39936
	global_load_lds_dwordx4 v[226:227], off
	v_lshl_add_u64 v[226:227], s[24:25], 0, v[132:133]
	s_mov_b32 m0, s42
	s_nop 0
	global_load_lds_dwordx4 v[226:227], off
	s_waitcnt vmcnt(8)
	s_waitcnt lgkmcnt(0)
	s_barrier
	s_setprio 1
	s_waitcnt lgkmcnt(0)
	v_mfma_f32_16x16x32_bf16 v[126:129], v[146:149], v[190:193], v[126:129]
	v_mfma_f32_16x16x32_bf16 v[126:129], v[150:153], v[194:197], v[126:129]
	v_mfma_f32_16x16x32_bf16 v[122:125], v[158:161], v[194:197], v[122:125]
	v_mfma_f32_16x16x32_bf16 v[122:125], v[154:157], v[190:193], v[122:125]
	v_mfma_f32_16x16x32_bf16 v[114:117], v[162:165], v[190:193], v[114:117]
	v_mfma_f32_16x16x32_bf16 v[114:117], v[166:169], v[194:197], v[114:117]
	v_mfma_f32_16x16x32_bf16 v[106:109], v[178:181], v[194:197], v[106:109]
	v_mfma_f32_16x16x32_bf16 v[106:109], v[170:173], v[190:193], v[106:109]
	v_mfma_f32_16x16x32_bf16 v[90:93], v[170:173], v[198:201], v[90:93]
	v_mfma_f32_16x16x32_bf16 v[90:93], v[178:181], v[202:205], v[90:93]
	v_mfma_f32_16x16x32_bf16 v[98:101], v[166:169], v[202:205], v[98:101]
	v_mfma_f32_16x16x32_bf16 v[98:101], v[162:165], v[198:201], v[98:101]
	v_mfma_f32_16x16x32_bf16 v[110:113], v[154:157], v[198:201], v[110:113]
	v_mfma_f32_16x16x32_bf16 v[110:113], v[158:161], v[202:205], v[110:113]
	v_mfma_f32_16x16x32_bf16 v[118:121], v[150:153], v[202:205], v[118:121]
	v_mfma_f32_16x16x32_bf16 v[118:121], v[146:149], v[198:201], v[118:121]
	s_setprio 0
	s_setprio 1
	v_mfma_f32_16x16x32_bf16 v[102:105], v[146:149], v[206:209], v[102:105]
	v_mfma_f32_16x16x32_bf16 v[102:105], v[150:153], v[228:231], v[102:105]
	v_mfma_f32_16x16x32_bf16 v[94:97], v[158:161], v[228:231], v[94:97]
	v_mfma_f32_16x16x32_bf16 v[94:97], v[154:157], v[206:209], v[94:97]
	v_mfma_f32_16x16x32_bf16 v[82:85], v[162:165], v[206:209], v[82:85]
	v_mfma_f32_16x16x32_bf16 v[82:85], v[166:169], v[228:231], v[82:85]
	v_mfma_f32_16x16x32_bf16 v[74:77], v[178:181], v[228:231], v[74:77]
	v_mfma_f32_16x16x32_bf16 v[74:77], v[170:173], v[206:209], v[74:77]
	v_mfma_f32_16x16x32_bf16 v[66:69], v[170:173], v[232:235], v[66:69]
	v_mfma_f32_16x16x32_bf16 v[66:69], v[178:181], v[236:239], v[66:69]
	v_mfma_f32_16x16x32_bf16 v[70:73], v[166:169], v[236:239], v[70:73]
	v_mfma_f32_16x16x32_bf16 v[70:73], v[162:165], v[232:235], v[70:73]
	v_mfma_f32_16x16x32_bf16 v[78:81], v[154:157], v[232:235], v[78:81]
	v_mfma_f32_16x16x32_bf16 v[78:81], v[158:161], v[236:239], v[78:81]
	v_mfma_f32_16x16x32_bf16 v[86:89], v[150:153], v[236:239], v[86:89]
	v_mfma_f32_16x16x32_bf16 v[86:89], v[146:149], v[232:235], v[86:89]
	s_setprio 0
	s_barrier
	s_add_i32 s24, s53, s38
	v_lshl_add_u64 v[140:141], v[140:141], 0, s[34:35]
	s_mov_b32 m0, s24
	ds_read_b128 v[190:193], v145 offset:49152
	ds_read_b128 v[194:197], v145 offset:50176
	ds_read_b128 v[198:201], v145 offset:51200
	ds_read_b128 v[202:205], v145 offset:52224
	ds_read_b128 v[206:209], v145 offset:53248
	ds_read_b128 v[228:231], v145 offset:54272
	ds_read_b128 v[232:235], v145 offset:55296
	ds_read_b128 v[236:239], v145 offset:56320
	global_load_lds_dwordx4 v[140:141], off
	s_add_i32 m0, s24, 0x2000
	s_add_u32 s22, s22, 0x100080
	v_lshl_add_u64 v[140:141], v[186:187], 0, s[34:35]
	s_addc_u32 s23, s23, 0
	s_add_i32 s24, s54, s38
	global_load_lds_dwordx4 v[140:141], off
	v_lshl_add_u64 v[140:141], s[22:23], 0, v[0:1]
	s_mov_b32 m0, s24
	s_nop 0
	global_load_lds_dwordx4 v[140:141], off
	v_lshl_add_u64 v[140:141], s[22:23], 0, v[130:131]
	s_add_i32 m0, s24, 0x2000
	s_nop 0
	global_load_lds_dwordx4 v[140:141], off
	v_lshl_add_u64 v[140:141], v[188:189], 0, s[34:35]
	s_mov_b32 m0, s43
	s_nop 0
	global_load_lds_dwordx4 v[140:141], off
	v_lshl_add_u64 v[140:141], v[210:211], 0, s[34:35]
	s_mov_b32 m0, s44
	s_nop 0
	global_load_lds_dwordx4 v[140:141], off
	s_waitcnt vmcnt(8)
	s_waitcnt lgkmcnt(0)
	s_barrier
	s_setprio 1
	s_waitcnt lgkmcnt(0)
	v_mfma_f32_16x16x32_bf16 v[62:65], v[146:149], v[190:193], v[62:65]
	v_mfma_f32_16x16x32_bf16 v[62:65], v[150:153], v[194:197], v[62:65]
	v_mfma_f32_16x16x32_bf16 v[58:61], v[158:161], v[194:197], v[58:61]
	v_mfma_f32_16x16x32_bf16 v[58:61], v[154:157], v[190:193], v[58:61]
	v_mfma_f32_16x16x32_bf16 v[50:53], v[162:165], v[190:193], v[50:53]
	v_mfma_f32_16x16x32_bf16 v[50:53], v[166:169], v[194:197], v[50:53]
	v_mfma_f32_16x16x32_bf16 v[42:45], v[178:181], v[194:197], v[42:45]
	v_mfma_f32_16x16x32_bf16 v[42:45], v[170:173], v[190:193], v[42:45]
	v_mfma_f32_16x16x32_bf16 v[26:29], v[170:173], v[198:201], v[26:29]
	v_mfma_f32_16x16x32_bf16 v[26:29], v[178:181], v[202:205], v[26:29]
	v_mfma_f32_16x16x32_bf16 v[34:37], v[166:169], v[202:205], v[34:37]
	v_mfma_f32_16x16x32_bf16 v[34:37], v[162:165], v[198:201], v[34:37]
	v_mfma_f32_16x16x32_bf16 v[46:49], v[154:157], v[198:201], v[46:49]
	v_mfma_f32_16x16x32_bf16 v[46:49], v[158:161], v[202:205], v[46:49]
	v_mfma_f32_16x16x32_bf16 v[54:57], v[150:153], v[202:205], v[54:57]
	v_mfma_f32_16x16x32_bf16 v[54:57], v[146:149], v[198:201], v[54:57]
	s_setprio 0
	s_setprio 1
	v_mfma_f32_16x16x32_bf16 v[38:41], v[146:149], v[206:209], v[38:41]
	v_mfma_f32_16x16x32_bf16 v[38:41], v[150:153], v[228:231], v[38:41]
	v_mfma_f32_16x16x32_bf16 v[30:33], v[158:161], v[228:231], v[30:33]
	v_mfma_f32_16x16x32_bf16 v[30:33], v[154:157], v[206:209], v[30:33]
	v_mfma_f32_16x16x32_bf16 v[18:21], v[162:165], v[206:209], v[18:21]
	v_mfma_f32_16x16x32_bf16 v[18:21], v[166:169], v[228:231], v[18:21]
	v_mfma_f32_16x16x32_bf16 v[10:13], v[178:181], v[228:231], v[10:13]
	v_mfma_f32_16x16x32_bf16 v[10:13], v[170:173], v[206:209], v[10:13]
	v_mfma_f32_16x16x32_bf16 v[2:5], v[170:173], v[232:235], v[2:5]
	v_mfma_f32_16x16x32_bf16 v[2:5], v[178:181], v[236:239], v[2:5]
	v_mfma_f32_16x16x32_bf16 v[6:9], v[166:169], v[236:239], v[6:9]
	v_mfma_f32_16x16x32_bf16 v[6:9], v[162:165], v[232:235], v[6:9]
	v_mfma_f32_16x16x32_bf16 v[14:17], v[154:157], v[232:235], v[14:17]
	v_mfma_f32_16x16x32_bf16 v[14:17], v[158:161], v[236:239], v[14:17]
	v_mfma_f32_16x16x32_bf16 v[22:25], v[150:153], v[236:239], v[22:25]
	v_mfma_f32_16x16x32_bf16 v[22:25], v[146:149], v[232:235], v[22:25]
	s_setprio 0
	s_barrier
	s_add_i32 s52, s52, 2
	s_add_u32 s18, s18, 0x100
	s_addc_u32 s19, s19, 0
	s_add_u32 s50, s50, 0x100
	s_addc_u32 s51, s51, 0
	s_cmp_gt_u32 s52, 61
	s_cbranch_scc0 .LBB0_575
	s_and_b64 vcc, exec, s[4:5]
	s_cbranch_vccz .LBB0_578
	s_barrier

.LBB0_721:
	s_add_u32 s18, s16, 0xfff00080
	s_addc_u32 s19, s17, -1
	s_add_i32 s53, 0, 0x10000
	s_cmp_eq_u32 s52, 60
	s_cselect_b32 s23, s7, s19
	s_cselect_b32 s22, s48, s18
	v_add_u32_e32 v140, s53, v143
	s_cselect_b32 s19, s5, s51
	s_cselect_b32 s18, s49, s50
	s_add_i32 s56, 0, 0x14000
	ds_read_b128 v[146:149], v140
	ds_read_b128 v[150:153], v140 offset:1024
	ds_read_b128 v[154:157], v140 offset:2048
	ds_read_b128 v[158:161], v140 offset:3072
	v_add_u32_e32 v140, s56, v143
	ds_read_b128 v[162:165], v140
	ds_read_b128 v[166:169], v140 offset:1024
	ds_read_b128 v[170:173], v140 offset:2048
	ds_read_b128 v[178:181], v140 offset:3072
	v_lshl_add_u64 v[140:141], s[16:17], 0, v[136:137]
	s_add_i32 m0, s31, 0xc000
	ds_read_b128 v[190:193], v145
	ds_read_b128 v[194:197], v145 offset:1024
	ds_read_b128 v[198:201], v145 offset:2048
	ds_read_b128 v[202:205], v145 offset:3072
	ds_read_b128 v[206:209], v145 offset:4096
	ds_read_b128 v[228:231], v145 offset:5120
	ds_read_b128 v[232:235], v145 offset:6144
	ds_read_b128 v[236:239], v145 offset:7168
	global_load_lds_dwordx4 v[140:141], off
	v_lshl_add_u64 v[140:141], s[16:17], 0, v[138:139]
	s_add_i32 m0, s31, 0xe000
	s_nop 0
	global_load_lds_dwordx4 v[140:141], off
	s_waitcnt vmcnt(8)
	s_waitcnt lgkmcnt(0)
	s_barrier
	s_setprio 1
	s_waitcnt lgkmcnt(0)
	v_mfma_f32_16x16x32_bf16 v[126:129], v[146:149], v[190:193], v[126:129]
	v_mfma_f32_16x16x32_bf16 v[126:129], v[150:153], v[194:197], v[126:129]
	v_mfma_f32_16x16x32_bf16 v[118:121], v[158:161], v[194:197], v[118:121]
	v_mfma_f32_16x16x32_bf16 v[118:121], v[154:157], v[190:193], v[118:121]
	v_mfma_f32_16x16x32_bf16 v[122:125], v[162:165], v[190:193], v[122:125]
	v_mfma_f32_16x16x32_bf16 v[122:125], v[166:169], v[194:197], v[122:125]
	v_mfma_f32_16x16x32_bf16 v[114:117], v[178:181], v[194:197], v[114:117]
	v_mfma_f32_16x16x32_bf16 v[114:117], v[170:173], v[190:193], v[114:117]
	v_mfma_f32_16x16x32_bf16 v[98:101], v[170:173], v[198:201], v[98:101]
	v_mfma_f32_16x16x32_bf16 v[98:101], v[178:181], v[202:205], v[98:101]
	v_mfma_f32_16x16x32_bf16 v[106:109], v[166:169], v[202:205], v[106:109]
	v_mfma_f32_16x16x32_bf16 v[106:109], v[162:165], v[198:201], v[106:109]
	v_mfma_f32_16x16x32_bf16 v[102:105], v[154:157], v[198:201], v[102:105]
	v_mfma_f32_16x16x32_bf16 v[102:105], v[158:161], v[202:205], v[102:105]
	v_mfma_f32_16x16x32_bf16 v[110:113], v[150:153], v[202:205], v[110:113]
	v_mfma_f32_16x16x32_bf16 v[110:113], v[146:149], v[198:201], v[110:113]
	s_setprio 0
	s_setprio 1
	v_mfma_f32_16x16x32_bf16 v[94:97], v[146:149], v[206:209], v[94:97]
	v_mfma_f32_16x16x32_bf16 v[94:97], v[150:153], v[228:231], v[94:97]
	v_mfma_f32_16x16x32_bf16 v[86:89], v[158:161], v[228:231], v[86:89]
	v_mfma_f32_16x16x32_bf16 v[86:89], v[154:157], v[206:209], v[86:89]
	v_mfma_f32_16x16x32_bf16 v[90:93], v[162:165], v[206:209], v[90:93]
	v_mfma_f32_16x16x32_bf16 v[90:93], v[166:169], v[228:231], v[90:93]
	v_mfma_f32_16x16x32_bf16 v[82:85], v[178:181], v[228:231], v[82:85]
	v_mfma_f32_16x16x32_bf16 v[82:85], v[170:173], v[206:209], v[82:85]
	v_mfma_f32_16x16x32_bf16 v[66:69], v[170:173], v[232:235], v[66:69]
	v_mfma_f32_16x16x32_bf16 v[66:69], v[178:181], v[236:239], v[66:69]
	v_mfma_f32_16x16x32_bf16 v[74:77], v[166:169], v[236:239], v[74:77]
	v_mfma_f32_16x16x32_bf16 v[74:77], v[162:165], v[232:235], v[74:77]
	v_mfma_f32_16x16x32_bf16 v[70:73], v[154:157], v[232:235], v[70:73]
	v_mfma_f32_16x16x32_bf16 v[70:73], v[158:161], v[236:239], v[70:73]
	v_mfma_f32_16x16x32_bf16 v[78:81], v[150:153], v[236:239], v[78:81]
	v_mfma_f32_16x16x32_bf16 v[78:81], v[146:149], v[232:235], v[78:81]
	s_setprio 0
	s_barrier
	s_add_i32 s53, s53, s26
	v_lshl_add_u64 v[140:141], s[18:19], 0, v[0:1]
	s_mov_b32 m0, s53
	ds_read_b128 v[190:193], v145 offset:16384
	ds_read_b128 v[194:197], v145 offset:17408
	ds_read_b128 v[198:201], v145 offset:18432
	ds_read_b128 v[202:205], v145 offset:19456
	ds_read_b128 v[206:209], v145 offset:20480
	ds_read_b128 v[228:231], v145 offset:21504
	ds_read_b128 v[232:235], v145 offset:22528
	ds_read_b128 v[236:239], v145 offset:23552
	global_load_lds_dwordx4 v[140:141], off
	s_add_i32 m0, s53, 0x2000
	s_add_u32 s54, s18, 0x100000
	v_lshl_add_u64 v[186:187], s[18:19], 0, v[130:131]
	s_addc_u32 s55, s19, 0
	s_add_i32 s53, s56, s26
	global_load_lds_dwordx4 v[186:187], off
	v_lshl_add_u64 v[188:189], s[54:55], 0, v[0:1]
	s_mov_b32 m0, s53
	v_lshl_add_u64 v[210:211], s[22:23], 0, v[132:133]
	global_load_lds_dwordx4 v[188:189], off
	v_lshl_add_u64 v[188:189], s[54:55], 0, v[130:131]
	s_add_i32 m0, s53, 0x2000
	s_nop 0
	global_load_lds_dwordx4 v[188:189], off
	v_lshl_add_u64 v[188:189], s[22:23], 0, v[134:135]
	s_mov_b32 m0, s31
	s_nop 0
	global_load_lds_dwordx4 v[188:189], off
	s_mov_b32 m0, s40
	s_nop 0
	global_load_lds_dwordx4 v[210:211], off
	s_waitcnt vmcnt(8)
	s_waitcnt lgkmcnt(0)
	s_barrier
	s_setprio 1
	s_waitcnt lgkmcnt(0)
	v_mfma_f32_16x16x32_bf16 v[62:65], v[146:149], v[190:193], v[62:65]
	v_mfma_f32_16x16x32_bf16 v[62:65], v[150:153], v[194:197], v[62:65]
	v_mfma_f32_16x16x32_bf16 v[54:57], v[158:161], v[194:197], v[54:57]
	v_mfma_f32_16x16x32_bf16 v[54:57], v[154:157], v[190:193], v[54:57]
	v_mfma_f32_16x16x32_bf16 v[58:61], v[162:165], v[190:193], v[58:61]
	v_mfma_f32_16x16x32_bf16 v[58:61], v[166:169], v[194:197], v[58:61]
	v_mfma_f32_16x16x32_bf16 v[50:53], v[178:181], v[194:197], v[50:53]
	v_mfma_f32_16x16x32_bf16 v[50:53], v[170:173], v[190:193], v[50:53]
	v_mfma_f32_16x16x32_bf16 v[34:37], v[170:173], v[198:201], v[34:37]
	v_mfma_f32_16x16x32_bf16 v[34:37], v[178:181], v[202:205], v[34:37]
	v_mfma_f32_16x16x32_bf16 v[42:45], v[166:169], v[202:205], v[42:45]
	v_mfma_f32_16x16x32_bf16 v[42:45], v[162:165], v[198:201], v[42:45]
	v_mfma_f32_16x16x32_bf16 v[38:41], v[154:157], v[198:201], v[38:41]
	v_mfma_f32_16x16x32_bf16 v[38:41], v[158:161], v[202:205], v[38:41]
	v_mfma_f32_16x16x32_bf16 v[46:49], v[150:153], v[202:205], v[46:49]
	v_mfma_f32_16x16x32_bf16 v[46:49], v[146:149], v[198:201], v[46:49]
	s_setprio 0
	s_setprio 1
	v_mfma_f32_16x16x32_bf16 v[30:33], v[146:149], v[206:209], v[30:33]
	v_mfma_f32_16x16x32_bf16 v[30:33], v[150:153], v[228:231], v[30:33]
	v_mfma_f32_16x16x32_bf16 v[22:25], v[158:161], v[228:231], v[22:25]
	v_mfma_f32_16x16x32_bf16 v[22:25], v[154:157], v[206:209], v[22:25]
	v_mfma_f32_16x16x32_bf16 v[26:29], v[162:165], v[206:209], v[26:29]
	v_mfma_f32_16x16x32_bf16 v[26:29], v[166:169], v[228:231], v[26:29]
	v_mfma_f32_16x16x32_bf16 v[18:21], v[178:181], v[228:231], v[18:21]
	v_mfma_f32_16x16x32_bf16 v[18:21], v[170:173], v[206:209], v[18:21]
	v_mfma_f32_16x16x32_bf16 v[2:5], v[170:173], v[232:235], v[2:5]
	v_mfma_f32_16x16x32_bf16 v[2:5], v[178:181], v[236:239], v[2:5]
	v_mfma_f32_16x16x32_bf16 v[10:13], v[166:169], v[236:239], v[10:13]
	v_mfma_f32_16x16x32_bf16 v[10:13], v[162:165], v[232:235], v[10:13]
	v_mfma_f32_16x16x32_bf16 v[6:9], v[154:157], v[232:235], v[6:9]
	v_mfma_f32_16x16x32_bf16 v[6:9], v[158:161], v[236:239], v[6:9]
	v_mfma_f32_16x16x32_bf16 v[14:17], v[150:153], v[236:239], v[14:17]
	v_mfma_f32_16x16x32_bf16 v[14:17], v[146:149], v[232:235], v[14:17]
	s_setprio 0
	s_barrier
	s_add_i32 s53, 0, 0x18000
	s_add_i32 s54, 0, 0x1c000
	v_add_u32_e32 v158, s53, v143
	v_add_u32_e32 v175, s54, v143
	ds_read_b128 v[146:149], v158
	ds_read_b128 v[150:153], v158 offset:1024
	ds_read_b128 v[154:157], v158 offset:2048
	ds_read_b128 v[158:161], v158 offset:3072
	ds_read_b128 v[162:165], v175
	ds_read_b128 v[166:169], v175 offset:1024
	ds_read_b128 v[170:173], v175 offset:2048
	ds_read_b128 v[178:181], v175 offset:3072
	s_add_u32 s22, s22, 0x100000
	s_addc_u32 s23, s23, 0
	s_mov_b32 m0, s41
	v_lshl_add_u64 v[226:227], s[22:23], 0, v[134:135]
	ds_read_b128 v[190:193], v145 offset:32768
	ds_read_b128 v[194:197], v145 offset:33792
	ds_read_b128 v[198:201], v145 offset:34816
	ds_read_b128 v[202:205], v145 offset:35840
	ds_read_b128 v[206:209], v145 offset:36864
	ds_read_b128 v[228:231], v145 offset:37888
	ds_read_b128 v[232:235], v145 offset:38912
	ds_read_b128 v[236:239], v145 offset:39936
	global_load_lds_dwordx4 v[226:227], off
	v_lshl_add_u64 v[226:227], s[22:23], 0, v[132:133]
	s_mov_b32 m0, s42
	s_nop 0
	global_load_lds_dwordx4 v[226:227], off
	s_waitcnt vmcnt(8)
	s_waitcnt lgkmcnt(0)
	s_barrier
	s_setprio 1
	s_waitcnt lgkmcnt(0)
	v_mfma_f32_16x16x32_bf16 v[126:129], v[146:149], v[190:193], v[126:129]
	v_mfma_f32_16x16x32_bf16 v[126:129], v[150:153], v[194:197], v[126:129]
	v_mfma_f32_16x16x32_bf16 v[118:121], v[158:161], v[194:197], v[118:121]
	v_mfma_f32_16x16x32_bf16 v[118:121], v[154:157], v[190:193], v[118:121]
	v_mfma_f32_16x16x32_bf16 v[122:125], v[162:165], v[190:193], v[122:125]
	v_mfma_f32_16x16x32_bf16 v[122:125], v[166:169], v[194:197], v[122:125]
	v_mfma_f32_16x16x32_bf16 v[114:117], v[178:181], v[194:197], v[114:117]
	v_mfma_f32_16x16x32_bf16 v[114:117], v[170:173], v[190:193], v[114:117]
	v_mfma_f32_16x16x32_bf16 v[98:101], v[170:173], v[198:201], v[98:101]
	v_mfma_f32_16x16x32_bf16 v[98:101], v[178:181], v[202:205], v[98:101]
	v_mfma_f32_16x16x32_bf16 v[106:109], v[166:169], v[202:205], v[106:109]
	v_mfma_f32_16x16x32_bf16 v[106:109], v[162:165], v[198:201], v[106:109]
	v_mfma_f32_16x16x32_bf16 v[102:105], v[154:157], v[198:201], v[102:105]
	v_mfma_f32_16x16x32_bf16 v[102:105], v[158:161], v[202:205], v[102:105]
	v_mfma_f32_16x16x32_bf16 v[110:113], v[150:153], v[202:205], v[110:113]
	v_mfma_f32_16x16x32_bf16 v[110:113], v[146:149], v[198:201], v[110:113]
	s_setprio 0
	s_setprio 1
	v_mfma_f32_16x16x32_bf16 v[94:97], v[146:149], v[206:209], v[94:97]
	v_mfma_f32_16x16x32_bf16 v[94:97], v[150:153], v[228:231], v[94:97]
	v_mfma_f32_16x16x32_bf16 v[86:89], v[158:161], v[228:231], v[86:89]
	v_mfma_f32_16x16x32_bf16 v[86:89], v[154:157], v[206:209], v[86:89]
	v_mfma_f32_16x16x32_bf16 v[90:93], v[162:165], v[206:209], v[90:93]
	v_mfma_f32_16x16x32_bf16 v[90:93], v[166:169], v[228:231], v[90:93]
	v_mfma_f32_16x16x32_bf16 v[82:85], v[178:181], v[228:231], v[82:85]
	v_mfma_f32_16x16x32_bf16 v[82:85], v[170:173], v[206:209], v[82:85]
	v_mfma_f32_16x16x32_bf16 v[66:69], v[170:173], v[232:235], v[66:69]
	v_mfma_f32_16x16x32_bf16 v[66:69], v[178:181], v[236:239], v[66:69]
	v_mfma_f32_16x16x32_bf16 v[74:77], v[166:169], v[236:239], v[74:77]
	v_mfma_f32_16x16x32_bf16 v[74:77], v[162:165], v[232:235], v[74:77]
	v_mfma_f32_16x16x32_bf16 v[70:73], v[154:157], v[232:235], v[70:73]
	v_mfma_f32_16x16x32_bf16 v[70:73], v[158:161], v[236:239], v[70:73]
	v_mfma_f32_16x16x32_bf16 v[78:81], v[150:153], v[236:239], v[78:81]
	v_mfma_f32_16x16x32_bf16 v[78:81], v[146:149], v[232:235], v[78:81]
	s_setprio 0
	s_barrier
	s_add_i32 s22, s53, s26
	v_lshl_add_u64 v[140:141], v[140:141], 0, s[34:35]
	s_mov_b32 m0, s22
	ds_read_b128 v[190:193], v145 offset:49152
	ds_read_b128 v[194:197], v145 offset:50176
	ds_read_b128 v[198:201], v145 offset:51200
	ds_read_b128 v[202:205], v145 offset:52224
	ds_read_b128 v[206:209], v145 offset:53248
	ds_read_b128 v[228:231], v145 offset:54272
	ds_read_b128 v[232:235], v145 offset:55296
	ds_read_b128 v[236:239], v145 offset:56320
	global_load_lds_dwordx4 v[140:141], off
	s_add_i32 m0, s22, 0x2000
	s_add_u32 s18, s18, 0x100080
	v_lshl_add_u64 v[140:141], v[186:187], 0, s[34:35]
	s_addc_u32 s19, s19, 0
	s_add_i32 s22, s54, s26
	global_load_lds_dwordx4 v[140:141], off
	v_lshl_add_u64 v[140:141], s[18:19], 0, v[0:1]
	s_mov_b32 m0, s22
	s_nop 0
	global_load_lds_dwordx4 v[140:141], off
	v_lshl_add_u64 v[140:141], s[18:19], 0, v[130:131]
	s_add_i32 m0, s22, 0x2000
	s_nop 0
	global_load_lds_dwordx4 v[140:141], off
	v_lshl_add_u64 v[140:141], v[188:189], 0, s[34:35]
	s_mov_b32 m0, s43
	s_nop 0
	global_load_lds_dwordx4 v[140:141], off
	v_lshl_add_u64 v[140:141], v[210:211], 0, s[34:35]
	s_mov_b32 m0, s44
	s_nop 0
	global_load_lds_dwordx4 v[140:141], off
	s_waitcnt vmcnt(8)
	s_waitcnt lgkmcnt(0)
	s_barrier
	s_setprio 1
	s_waitcnt lgkmcnt(0)
	v_mfma_f32_16x16x32_bf16 v[62:65], v[146:149], v[190:193], v[62:65]
	v_mfma_f32_16x16x32_bf16 v[62:65], v[150:153], v[194:197], v[62:65]
	v_mfma_f32_16x16x32_bf16 v[54:57], v[158:161], v[194:197], v[54:57]
	v_mfma_f32_16x16x32_bf16 v[54:57], v[154:157], v[190:193], v[54:57]
	v_mfma_f32_16x16x32_bf16 v[58:61], v[162:165], v[190:193], v[58:61]
	v_mfma_f32_16x16x32_bf16 v[58:61], v[166:169], v[194:197], v[58:61]
	v_mfma_f32_16x16x32_bf16 v[50:53], v[178:181], v[194:197], v[50:53]
	v_mfma_f32_16x16x32_bf16 v[50:53], v[170:173], v[190:193], v[50:53]
	v_mfma_f32_16x16x32_bf16 v[34:37], v[170:173], v[198:201], v[34:37]
	v_mfma_f32_16x16x32_bf16 v[34:37], v[178:181], v[202:205], v[34:37]
	v_mfma_f32_16x16x32_bf16 v[42:45], v[166:169], v[202:205], v[42:45]
	v_mfma_f32_16x16x32_bf16 v[42:45], v[162:165], v[198:201], v[42:45]
	v_mfma_f32_16x16x32_bf16 v[38:41], v[154:157], v[198:201], v[38:41]
	v_mfma_f32_16x16x32_bf16 v[38:41], v[158:161], v[202:205], v[38:41]
	v_mfma_f32_16x16x32_bf16 v[46:49], v[150:153], v[202:205], v[46:49]
	v_mfma_f32_16x16x32_bf16 v[46:49], v[146:149], v[198:201], v[46:49]
	s_setprio 0
	s_setprio 1
	v_mfma_f32_16x16x32_bf16 v[30:33], v[146:149], v[206:209], v[30:33]
	v_mfma_f32_16x16x32_bf16 v[30:33], v[150:153], v[228:231], v[30:33]
	v_mfma_f32_16x16x32_bf16 v[22:25], v[158:161], v[228:231], v[22:25]
	v_mfma_f32_16x16x32_bf16 v[22:25], v[154:157], v[206:209], v[22:25]
	v_mfma_f32_16x16x32_bf16 v[26:29], v[162:165], v[206:209], v[26:29]
	v_mfma_f32_16x16x32_bf16 v[26:29], v[166:169], v[228:231], v[26:29]
	v_mfma_f32_16x16x32_bf16 v[18:21], v[178:181], v[228:231], v[18:21]
	v_mfma_f32_16x16x32_bf16 v[18:21], v[170:173], v[206:209], v[18:21]
	v_mfma_f32_16x16x32_bf16 v[2:5], v[170:173], v[232:235], v[2:5]
	v_mfma_f32_16x16x32_bf16 v[2:5], v[178:181], v[236:239], v[2:5]
	v_mfma_f32_16x16x32_bf16 v[10:13], v[166:169], v[236:239], v[10:13]
	v_mfma_f32_16x16x32_bf16 v[10:13], v[162:165], v[232:235], v[10:13]
	v_mfma_f32_16x16x32_bf16 v[6:9], v[154:157], v[232:235], v[6:9]
	v_mfma_f32_16x16x32_bf16 v[6:9], v[158:161], v[236:239], v[6:9]
	v_mfma_f32_16x16x32_bf16 v[14:17], v[150:153], v[236:239], v[14:17]
	v_mfma_f32_16x16x32_bf16 v[14:17], v[146:149], v[232:235], v[14:17]
	s_setprio 0
	s_barrier
	s_add_i32 s52, s52, 2
	s_add_u32 s16, s16, 0x100
	s_addc_u32 s17, s17, 0
	s_add_u32 s50, s50, 0x100
	s_addc_u32 s51, s51, 0
	s_cmp_gt_u32 s52, 61
	s_cbranch_scc0 .LBB0_721
	s_and_b64 vcc, exec, s[2:3]
	s_cbranch_vccz .LBB0_724
	s_barrier

.LBB0_805:
	s_add_u32 s16, s14, 0x100
	s_addc_u32 s17, s15, 0
	s_add_i32 s49, 0, 0x10000
	s_cmpk_eq_i32 s48, 0xa8
	s_cselect_b32 s23, s5, s17
	s_cselect_b32 s22, s4, s16
	v_add_u32_e32 v140, s49, v143
	s_cselect_b32 s19, s9, s47
	s_cselect_b32 s18, s8, s46
	s_add_i32 s50, 0, 0x14000
	ds_read_b128 v[146:149], v140
	ds_read_b128 v[150:153], v140 offset:1024
	ds_read_b128 v[154:157], v140 offset:2048
	ds_read_b128 v[158:161], v140 offset:3072
	v_add_u32_e32 v140, s50, v143
	ds_read_b128 v[162:165], v140
	ds_read_b128 v[166:169], v140 offset:1024
	ds_read_b128 v[170:173], v140 offset:2048
	ds_read_b128 v[178:181], v140 offset:3072
	v_lshl_add_u64 v[140:141], s[14:15], 0, v[136:137]
	s_add_i32 m0, s31, 0xc000
	ds_read_b128 v[190:193], v145
	ds_read_b128 v[194:197], v145 offset:1024
	ds_read_b128 v[198:201], v145 offset:2048
	ds_read_b128 v[202:205], v145 offset:3072
	ds_read_b128 v[206:209], v145 offset:4096
	ds_read_b128 v[228:231], v145 offset:5120
	ds_read_b128 v[232:235], v145 offset:6144
	ds_read_b128 v[236:239], v145 offset:7168
	global_load_lds_dwordx4 v[140:141], off
	v_lshl_add_u64 v[140:141], s[14:15], 0, v[138:139]
	s_add_i32 m0, s31, 0xe000
	s_nop 0
	global_load_lds_dwordx4 v[140:141], off
	s_waitcnt vmcnt(8)
	s_waitcnt lgkmcnt(0)
	s_barrier
	s_setprio 1
	s_waitcnt lgkmcnt(0)
	v_mfma_f32_16x16x32_bf16 v[126:129], v[146:149], v[190:193], v[126:129]
	v_mfma_f32_16x16x32_bf16 v[126:129], v[150:153], v[194:197], v[126:129]
	v_mfma_f32_16x16x32_bf16 v[122:125], v[158:161], v[194:197], v[122:125]
	v_mfma_f32_16x16x32_bf16 v[122:125], v[154:157], v[190:193], v[122:125]
	v_mfma_f32_16x16x32_bf16 v[114:117], v[162:165], v[190:193], v[114:117]
	v_mfma_f32_16x16x32_bf16 v[114:117], v[166:169], v[194:197], v[114:117]
	v_mfma_f32_16x16x32_bf16 v[106:109], v[178:181], v[194:197], v[106:109]
	v_mfma_f32_16x16x32_bf16 v[106:109], v[170:173], v[190:193], v[106:109]
	v_mfma_f32_16x16x32_bf16 v[90:93], v[170:173], v[198:201], v[90:93]
	v_mfma_f32_16x16x32_bf16 v[90:93], v[178:181], v[202:205], v[90:93]
	v_mfma_f32_16x16x32_bf16 v[98:101], v[166:169], v[202:205], v[98:101]
	v_mfma_f32_16x16x32_bf16 v[98:101], v[162:165], v[198:201], v[98:101]
	v_mfma_f32_16x16x32_bf16 v[110:113], v[154:157], v[198:201], v[110:113]
	v_mfma_f32_16x16x32_bf16 v[110:113], v[158:161], v[202:205], v[110:113]
	v_mfma_f32_16x16x32_bf16 v[118:121], v[150:153], v[202:205], v[118:121]
	v_mfma_f32_16x16x32_bf16 v[118:121], v[146:149], v[198:201], v[118:121]
	s_setprio 0
	s_setprio 1
	v_mfma_f32_16x16x32_bf16 v[102:105], v[146:149], v[206:209], v[102:105]
	v_mfma_f32_16x16x32_bf16 v[102:105], v[150:153], v[228:231], v[102:105]
	v_mfma_f32_16x16x32_bf16 v[94:97], v[158:161], v[228:231], v[94:97]
	v_mfma_f32_16x16x32_bf16 v[94:97], v[154:157], v[206:209], v[94:97]
	v_mfma_f32_16x16x32_bf16 v[82:85], v[162:165], v[206:209], v[82:85]
	v_mfma_f32_16x16x32_bf16 v[82:85], v[166:169], v[228:231], v[82:85]
	v_mfma_f32_16x16x32_bf16 v[74:77], v[178:181], v[228:231], v[74:77]
	v_mfma_f32_16x16x32_bf16 v[74:77], v[170:173], v[206:209], v[74:77]
	v_mfma_f32_16x16x32_bf16 v[66:69], v[170:173], v[232:235], v[66:69]
	v_mfma_f32_16x16x32_bf16 v[66:69], v[178:181], v[236:239], v[66:69]
	v_mfma_f32_16x16x32_bf16 v[70:73], v[166:169], v[236:239], v[70:73]
	v_mfma_f32_16x16x32_bf16 v[70:73], v[162:165], v[232:235], v[70:73]
	v_mfma_f32_16x16x32_bf16 v[78:81], v[154:157], v[232:235], v[78:81]
	v_mfma_f32_16x16x32_bf16 v[78:81], v[158:161], v[236:239], v[78:81]
	v_mfma_f32_16x16x32_bf16 v[86:89], v[150:153], v[236:239], v[86:89]
	v_mfma_f32_16x16x32_bf16 v[86:89], v[146:149], v[232:235], v[86:89]
	s_setprio 0
	s_barrier
	s_add_i32 s14, s49, s26
	v_lshl_add_u64 v[140:141], s[18:19], 0, v[0:1]
	s_mov_b32 m0, s14
	ds_read_b128 v[190:193], v145 offset:16384
	ds_read_b128 v[194:197], v145 offset:17408
	ds_read_b128 v[198:201], v145 offset:18432
	ds_read_b128 v[202:205], v145 offset:19456
	ds_read_b128 v[206:209], v145 offset:20480
	ds_read_b128 v[228:231], v145 offset:21504
	ds_read_b128 v[232:235], v145 offset:22528
	ds_read_b128 v[236:239], v145 offset:23552
	global_load_lds_dwordx4 v[140:141], off
	s_add_i32 m0, s14, 0x2000
	s_add_u32 s14, s18, 0x2b0000
	v_lshl_add_u64 v[186:187], s[18:19], 0, v[130:131]
	s_addc_u32 s15, s19, 0
	s_add_i32 s49, s50, s26
	global_load_lds_dwordx4 v[186:187], off
	v_lshl_add_u64 v[188:189], s[14:15], 0, v[0:1]
	s_mov_b32 m0, s49
	v_lshl_add_u64 v[210:211], s[22:23], 0, v[132:133]
	global_load_lds_dwordx4 v[188:189], off
	v_lshl_add_u64 v[188:189], s[14:15], 0, v[130:131]
	s_add_i32 m0, s49, 0x2000
	s_nop 0
	global_load_lds_dwordx4 v[188:189], off
	v_lshl_add_u64 v[188:189], s[22:23], 0, v[134:135]
	s_mov_b32 m0, s31
	s_nop 0
	global_load_lds_dwordx4 v[188:189], off
	s_mov_b32 m0, s36
	s_nop 0
	global_load_lds_dwordx4 v[210:211], off
	s_waitcnt vmcnt(8)
	s_waitcnt lgkmcnt(0)
	s_barrier
	s_setprio 1
	s_waitcnt lgkmcnt(0)
	v_mfma_f32_16x16x32_bf16 v[62:65], v[146:149], v[190:193], v[62:65]
	v_mfma_f32_16x16x32_bf16 v[62:65], v[150:153], v[194:197], v[62:65]
	v_mfma_f32_16x16x32_bf16 v[58:61], v[158:161], v[194:197], v[58:61]
	v_mfma_f32_16x16x32_bf16 v[58:61], v[154:157], v[190:193], v[58:61]
	v_mfma_f32_16x16x32_bf16 v[50:53], v[162:165], v[190:193], v[50:53]
	v_mfma_f32_16x16x32_bf16 v[50:53], v[166:169], v[194:197], v[50:53]
	v_mfma_f32_16x16x32_bf16 v[42:45], v[178:181], v[194:197], v[42:45]
	v_mfma_f32_16x16x32_bf16 v[42:45], v[170:173], v[190:193], v[42:45]
	v_mfma_f32_16x16x32_bf16 v[26:29], v[170:173], v[198:201], v[26:29]
	v_mfma_f32_16x16x32_bf16 v[26:29], v[178:181], v[202:205], v[26:29]
	v_mfma_f32_16x16x32_bf16 v[34:37], v[166:169], v[202:205], v[34:37]
	v_mfma_f32_16x16x32_bf16 v[34:37], v[162:165], v[198:201], v[34:37]
	v_mfma_f32_16x16x32_bf16 v[46:49], v[154:157], v[198:201], v[46:49]
	v_mfma_f32_16x16x32_bf16 v[46:49], v[158:161], v[202:205], v[46:49]
	v_mfma_f32_16x16x32_bf16 v[54:57], v[150:153], v[202:205], v[54:57]
	v_mfma_f32_16x16x32_bf16 v[54:57], v[146:149], v[198:201], v[54:57]
	s_setprio 0
	s_setprio 1
	v_mfma_f32_16x16x32_bf16 v[38:41], v[146:149], v[206:209], v[38:41]
	v_mfma_f32_16x16x32_bf16 v[38:41], v[150:153], v[228:231], v[38:41]
	v_mfma_f32_16x16x32_bf16 v[30:33], v[158:161], v[228:231], v[30:33]
	v_mfma_f32_16x16x32_bf16 v[30:33], v[154:157], v[206:209], v[30:33]
	v_mfma_f32_16x16x32_bf16 v[18:21], v[162:165], v[206:209], v[18:21]
	v_mfma_f32_16x16x32_bf16 v[18:21], v[166:169], v[228:231], v[18:21]
	v_mfma_f32_16x16x32_bf16 v[10:13], v[178:181], v[228:231], v[10:13]
	v_mfma_f32_16x16x32_bf16 v[10:13], v[170:173], v[206:209], v[10:13]
	v_mfma_f32_16x16x32_bf16 v[2:5], v[170:173], v[232:235], v[2:5]
	v_mfma_f32_16x16x32_bf16 v[2:5], v[178:181], v[236:239], v[2:5]
	v_mfma_f32_16x16x32_bf16 v[6:9], v[166:169], v[236:239], v[6:9]
	v_mfma_f32_16x16x32_bf16 v[6:9], v[162:165], v[232:235], v[6:9]
	v_mfma_f32_16x16x32_bf16 v[14:17], v[154:157], v[232:235], v[14:17]
	v_mfma_f32_16x16x32_bf16 v[14:17], v[158:161], v[236:239], v[14:17]
	v_mfma_f32_16x16x32_bf16 v[22:25], v[150:153], v[236:239], v[22:25]
	v_mfma_f32_16x16x32_bf16 v[22:25], v[146:149], v[232:235], v[22:25]
	s_setprio 0
	s_barrier
	s_add_i32 s49, 0, 0x18000
	s_add_i32 s50, 0, 0x1c000
	v_add_u32_e32 v158, s49, v143
	v_add_u32_e32 v175, s50, v143
	ds_read_b128 v[146:149], v158
	ds_read_b128 v[150:153], v158 offset:1024
	ds_read_b128 v[154:157], v158 offset:2048
	ds_read_b128 v[158:161], v158 offset:3072
	ds_read_b128 v[162:165], v175
	ds_read_b128 v[166:169], v175 offset:1024
	ds_read_b128 v[170:173], v175 offset:2048
	ds_read_b128 v[178:181], v175 offset:3072
	s_add_u32 s14, s22, 0x2b0000
	s_addc_u32 s15, s23, 0
	s_mov_b32 m0, s37
	v_lshl_add_u64 v[226:227], s[14:15], 0, v[134:135]
	ds_read_b128 v[190:193], v145 offset:32768
	ds_read_b128 v[194:197], v145 offset:33792
	ds_read_b128 v[198:201], v145 offset:34816
	ds_read_b128 v[202:205], v145 offset:35840
	ds_read_b128 v[206:209], v145 offset:36864
	ds_read_b128 v[228:231], v145 offset:37888
	ds_read_b128 v[232:235], v145 offset:38912
	ds_read_b128 v[236:239], v145 offset:39936
	global_load_lds_dwordx4 v[226:227], off
	v_lshl_add_u64 v[226:227], s[14:15], 0, v[132:133]
	s_mov_b32 m0, s38
	s_nop 0
	global_load_lds_dwordx4 v[226:227], off
	s_waitcnt vmcnt(8)
	s_waitcnt lgkmcnt(0)
	s_barrier
	s_setprio 1
	s_waitcnt lgkmcnt(0)
	v_mfma_f32_16x16x32_bf16 v[126:129], v[146:149], v[190:193], v[126:129]
	v_mfma_f32_16x16x32_bf16 v[126:129], v[150:153], v[194:197], v[126:129]
	v_mfma_f32_16x16x32_bf16 v[122:125], v[158:161], v[194:197], v[122:125]
	v_mfma_f32_16x16x32_bf16 v[122:125], v[154:157], v[190:193], v[122:125]
	v_mfma_f32_16x16x32_bf16 v[114:117], v[162:165], v[190:193], v[114:117]
	v_mfma_f32_16x16x32_bf16 v[114:117], v[166:169], v[194:197], v[114:117]
	v_mfma_f32_16x16x32_bf16 v[106:109], v[178:181], v[194:197], v[106:109]
	v_mfma_f32_16x16x32_bf16 v[106:109], v[170:173], v[190:193], v[106:109]
	v_mfma_f32_16x16x32_bf16 v[90:93], v[170:173], v[198:201], v[90:93]
	v_mfma_f32_16x16x32_bf16 v[90:93], v[178:181], v[202:205], v[90:93]
	v_mfma_f32_16x16x32_bf16 v[98:101], v[166:169], v[202:205], v[98:101]
	v_mfma_f32_16x16x32_bf16 v[98:101], v[162:165], v[198:201], v[98:101]
	v_mfma_f32_16x16x32_bf16 v[110:113], v[154:157], v[198:201], v[110:113]
	v_mfma_f32_16x16x32_bf16 v[110:113], v[158:161], v[202:205], v[110:113]
	v_mfma_f32_16x16x32_bf16 v[118:121], v[150:153], v[202:205], v[118:121]
	v_mfma_f32_16x16x32_bf16 v[118:121], v[146:149], v[198:201], v[118:121]
	s_setprio 0
	s_setprio 1
	v_mfma_f32_16x16x32_bf16 v[102:105], v[146:149], v[206:209], v[102:105]
	v_mfma_f32_16x16x32_bf16 v[102:105], v[150:153], v[228:231], v[102:105]
	v_mfma_f32_16x16x32_bf16 v[94:97], v[158:161], v[228:231], v[94:97]
	v_mfma_f32_16x16x32_bf16 v[94:97], v[154:157], v[206:209], v[94:97]
	v_mfma_f32_16x16x32_bf16 v[82:85], v[162:165], v[206:209], v[82:85]
	v_mfma_f32_16x16x32_bf16 v[82:85], v[166:169], v[228:231], v[82:85]
	v_mfma_f32_16x16x32_bf16 v[74:77], v[178:181], v[228:231], v[74:77]
	v_mfma_f32_16x16x32_bf16 v[74:77], v[170:173], v[206:209], v[74:77]
	v_mfma_f32_16x16x32_bf16 v[66:69], v[170:173], v[232:235], v[66:69]
	v_mfma_f32_16x16x32_bf16 v[66:69], v[178:181], v[236:239], v[66:69]
	v_mfma_f32_16x16x32_bf16 v[70:73], v[166:169], v[236:239], v[70:73]
	v_mfma_f32_16x16x32_bf16 v[70:73], v[162:165], v[232:235], v[70:73]
	v_mfma_f32_16x16x32_bf16 v[78:81], v[154:157], v[232:235], v[78:81]
	v_mfma_f32_16x16x32_bf16 v[78:81], v[158:161], v[236:239], v[78:81]
	v_mfma_f32_16x16x32_bf16 v[86:89], v[150:153], v[236:239], v[86:89]
	v_mfma_f32_16x16x32_bf16 v[86:89], v[146:149], v[232:235], v[86:89]
	s_setprio 0
	s_barrier
	s_add_i32 s14, s49, s26
	v_lshl_add_u64 v[140:141], v[140:141], 0, s[34:35]
	s_mov_b32 m0, s14
	ds_read_b128 v[190:193], v145 offset:49152
	ds_read_b128 v[194:197], v145 offset:50176
	ds_read_b128 v[198:201], v145 offset:51200
	ds_read_b128 v[202:205], v145 offset:52224
	ds_read_b128 v[206:209], v145 offset:53248
	ds_read_b128 v[228:231], v145 offset:54272
	ds_read_b128 v[232:235], v145 offset:55296
	ds_read_b128 v[236:239], v145 offset:56320
	global_load_lds_dwordx4 v[140:141], off
	s_add_i32 m0, s14, 0x2000
	s_add_u32 s14, s18, 0x2b0080
	v_lshl_add_u64 v[140:141], v[186:187], 0, s[34:35]
	s_addc_u32 s15, s19, 0
	s_add_i32 s18, s50, s26
	global_load_lds_dwordx4 v[140:141], off
	v_lshl_add_u64 v[140:141], s[14:15], 0, v[0:1]
	s_mov_b32 m0, s18
	s_nop 0
	global_load_lds_dwordx4 v[140:141], off
	v_lshl_add_u64 v[140:141], s[14:15], 0, v[130:131]
	s_add_i32 m0, s18, 0x2000
	s_nop 0
	global_load_lds_dwordx4 v[140:141], off
	v_lshl_add_u64 v[140:141], v[188:189], 0, s[34:35]
	s_mov_b32 m0, s39
	s_nop 0
	global_load_lds_dwordx4 v[140:141], off
	v_lshl_add_u64 v[140:141], v[210:211], 0, s[34:35]
	s_mov_b32 m0, s40
	s_nop 0
	global_load_lds_dwordx4 v[140:141], off
	s_waitcnt vmcnt(8)
	s_waitcnt lgkmcnt(0)
	s_barrier
	s_setprio 1
	s_waitcnt lgkmcnt(0)
	v_mfma_f32_16x16x32_bf16 v[62:65], v[146:149], v[190:193], v[62:65]
	v_mfma_f32_16x16x32_bf16 v[62:65], v[150:153], v[194:197], v[62:65]
	v_mfma_f32_16x16x32_bf16 v[58:61], v[158:161], v[194:197], v[58:61]
	v_mfma_f32_16x16x32_bf16 v[58:61], v[154:157], v[190:193], v[58:61]
	v_mfma_f32_16x16x32_bf16 v[50:53], v[162:165], v[190:193], v[50:53]
	v_mfma_f32_16x16x32_bf16 v[50:53], v[166:169], v[194:197], v[50:53]
	v_mfma_f32_16x16x32_bf16 v[42:45], v[178:181], v[194:197], v[42:45]
	v_mfma_f32_16x16x32_bf16 v[42:45], v[170:173], v[190:193], v[42:45]
	v_mfma_f32_16x16x32_bf16 v[26:29], v[170:173], v[198:201], v[26:29]
	v_mfma_f32_16x16x32_bf16 v[26:29], v[178:181], v[202:205], v[26:29]
	v_mfma_f32_16x16x32_bf16 v[34:37], v[166:169], v[202:205], v[34:37]
	v_mfma_f32_16x16x32_bf16 v[34:37], v[162:165], v[198:201], v[34:37]
	v_mfma_f32_16x16x32_bf16 v[46:49], v[154:157], v[198:201], v[46:49]
	v_mfma_f32_16x16x32_bf16 v[46:49], v[158:161], v[202:205], v[46:49]
	v_mfma_f32_16x16x32_bf16 v[54:57], v[150:153], v[202:205], v[54:57]
	v_mfma_f32_16x16x32_bf16 v[54:57], v[146:149], v[198:201], v[54:57]
	s_setprio 0
	s_setprio 1
	v_mfma_f32_16x16x32_bf16 v[38:41], v[146:149], v[206:209], v[38:41]
	v_mfma_f32_16x16x32_bf16 v[38:41], v[150:153], v[228:231], v[38:41]
	v_mfma_f32_16x16x32_bf16 v[30:33], v[158:161], v[228:231], v[30:33]
	v_mfma_f32_16x16x32_bf16 v[30:33], v[154:157], v[206:209], v[30:33]
	v_mfma_f32_16x16x32_bf16 v[18:21], v[162:165], v[206:209], v[18:21]
	v_mfma_f32_16x16x32_bf16 v[18:21], v[166:169], v[228:231], v[18:21]
	v_mfma_f32_16x16x32_bf16 v[10:13], v[178:181], v[228:231], v[10:13]
	v_mfma_f32_16x16x32_bf16 v[10:13], v[170:173], v[206:209], v[10:13]
	v_mfma_f32_16x16x32_bf16 v[2:5], v[170:173], v[232:235], v[2:5]
	v_mfma_f32_16x16x32_bf16 v[2:5], v[178:181], v[236:239], v[2:5]
	v_mfma_f32_16x16x32_bf16 v[6:9], v[166:169], v[236:239], v[6:9]
	v_mfma_f32_16x16x32_bf16 v[6:9], v[162:165], v[232:235], v[6:9]
	v_mfma_f32_16x16x32_bf16 v[14:17], v[154:157], v[232:235], v[14:17]
	v_mfma_f32_16x16x32_bf16 v[14:17], v[158:161], v[236:239], v[14:17]
	v_mfma_f32_16x16x32_bf16 v[22:25], v[150:153], v[236:239], v[22:25]
	v_mfma_f32_16x16x32_bf16 v[22:25], v[146:149], v[232:235], v[22:25]
	s_setprio 0
	s_barrier
	s_add_i32 s48, s48, 2
	s_add_u32 s46, s46, 0x100
	s_addc_u32 s47, s47, 0
	s_cmpk_gt_u32 s48, 0xa9
	s_mov_b64 s[14:15], s[16:17]
	s_cbranch_scc0 .LBB0_805
	s_and_b64 vcc, exec, s[6:7]
	s_cbranch_vccz .LBB0_808
	s_barrier
